# P5 pre-pass: the 72 workgroups idle in the SchedC/Sched1a stage run their first 12 P5 rows per wave there (same code), P5 proper starts at row 12 for them
# baseline (speedup 1.0000x reference)
;     __device__ __forceinline__ bool next(int i, Unit& u) const { const int L = i * G + (G - 1 - c); if (L >= 3264) return false; tile_map(L, 136, 24, u.pm, u.pn); u.pn += 4;     u.kh = 0; u.type = 0; return true; }
;     __device__ __forceinline__ bool next(int i, Unit& u) const { const int L = i * G + (G - 1 - c); if (L >= 2176) return false; tile_map(L, 136, 16, u.pm, u.pn); u.pn += 24; u.kh = 0; u.type = 0; return true; }
;     __device__ __forceinline__ bool next(int i, Unit& u) const { const int L = (i >> 1) * G + c; if (L >= 1024) return false; tile_map(L, 128, 8, u.pm, u.pn); u.kh = i & 1; u.type = 0; return true; }
;     __device__ __forceinline__ bool next(int i, Unit& u) const { const int L = (i >> 1) * G + c; if (L >= 128) return false; tile_map(L, 16, 8, u.pm, u.pn); u.pm += 120; u.kh = i & 1; u.type = 1; return true; }
; template <int MODE  , class Epi, class Sched>
; __device__ __forceinline__ void gemm_phase(LAS unsigned char* lds, const GemmDesc g, const Sched& S, const Epi& E) {
;     ...
;     if (!S.next(0, cur)) return;
; __device__ __forceinline__ void phase5(const Params& p) {
;     int t_ = threadIdx.x; asm volatile("" : "+v"(t_));
;     const int lane = t_ & 63, gw = blockIdx.x * 8 + (t_ >> 6), nw = gridDim.x * 8;
;     const bf16_t* DL = (const bf16_t*)(p.ws + WS_H);
;     int r = gw;
;     for (; r + nw < T; r += 2 * nw) p5_rows<2>(p, DL, r, nw, lane);
;     if (r < T) p5_rows<1>(p, DL, r, nw, lane);
.LBB0_1146:
	s_cmpk_gt_u32 s30, 0x5bf
	s_cbranch_scc0 .Lp5pre_skip
	s_cmpk_eq_u32 s33, 0x100
	s_cbranch_scc1 .Lp5pre_begin

; __device__ __forceinline__ float bf_lo(unsigned w) { return __uint_as_float(w << 16); }
; __device__ __forceinline__ float bf_hi(unsigned w) { return __uint_as_float(w & 0xffff0000u); }
; template <int NR>
; __device__ __forceinline__ void p5_rows(const Params& p, const bf16_t* __restrict__ DL, int r, int nw, int lane) {
;     f32x4 v[NR][8]; u32x4 d[NR][4];
; #pragma unroll
;     for (int k = 0; k < NR; ++k) { const int row = r + k * nw; const float* x = row < TP ? p.xp + (size_t)row * D : p.xs + (size_t)(row - TP) * D;
; #pragma unroll
;         for (int i = 0; i < 4; ++i) { v[k][2 * i] = *(const f32x4*)(x + (i * 64 + lane) * 8); v[k][2 * i + 1] = *(const f32x4*)(x + (i * 64 + lane) * 8 + 4);
;             d[k][i] = *(const u32x4*)(DL + (size_t)row * LDP + (i * 64 + lane) * 8); } }
; #pragma unroll
;     for (int k = 0; k < NR; ++k) { const int row = r + k * nw; float ss = 0.f;
; #pragma unroll
;         for (int i = 0; i < 4; ++i) { const u32x4 w = d[k][i];
;             v[k][2 * i] += (f32x4){bf_lo(w.x), bf_hi(w.x), bf_lo(w.y), bf_hi(w.y)}; v[k][2 * i + 1] += (f32x4){bf_lo(w.z), bf_hi(w.z), bf_lo(w.w), bf_hi(w.w)}; }
; #pragma unroll
;         for (int i = 0; i < 8; ++i) ss += (v[k][i][0] * v[k][i][0] + v[k][i][1] * v[k][i][1]) + (v[k][i][2] * v[k][i][2] + v[k][i][3] * v[k][i][3]);
; #pragma unroll
;         for (int o = 32; o >= 1; o >>= 1) ss += __shfl_xor(ss, o);
;         const float rs = rsqrtf(ss * (1.0f / D) + EPS);
; __device__ __forceinline__ void phase5(const Params& p) {
;     int t_ = threadIdx.x; asm volatile("" : "+v"(t_));
;     const int lane = t_ & 63, gw = blockIdx.x * 8 + (t_ >> 6), nw = gridDim.x * 8;
;     const bf16_t* DL = (const bf16_t*)(p.ws + WS_H);
;     int r = gw;
;     for (; r + nw < T; r += 2 * nw) p5_rows<2>(p, DL, r, nw, lane);
;     if (r < T) p5_rows<1>(p, DL, r, nw, lane);
.Lp5pre_begin:
	v_mov_b32_e32 v232, v0
	s_mov_b32 s0, 0x6000
	v_ashrrev_i32_e32 v95, 6, v0
	v_add_u32_e32 v70, s30, v95
	v_and_b32_e32 v1, 63, v0
	v_add_u32_e32 v6, s74, v70
	v_cmp_gt_i32_e32 vcc, s0, v6
	v_lshlrev_b32_e32 v68, 5, v1
	v_lshlrev_b32_e32 v72, 4, v1
	s_and_saveexec_b64 s[0:1], vcc
	s_cbranch_execz .Lp5pre_1198
	v_lshlrev_b32_e32 v0, 3, v1
	v_mbcnt_hi_u32_b32 v1, -1, v190
	v_and_b32_e32 v3, 64, v1
	v_add_u32_e32 v3, 64, v3
	v_xor_b32_e32 v5, 32, v1
	v_cmp_lt_i32_e32 vcc, v5, v3
	v_or_b32_e32 v2, 0x400, v0
	v_mov_b32_e32 v75, 0
	v_cndmask_b32_e32 v5, v1, v5, vcc
	v_lshlrev_b32_e32 v100, 2, v5
	v_xor_b32_e32 v5, 16, v1
	v_cmp_lt_i32_e32 vcc, v5, v3
	v_or_b32_e32 v4, 0x600, v0
	s_lshl_b32 s2, s33, 4
	v_cndmask_b32_e32 v5, v1, v5, vcc
	v_lshlrev_b32_e32 v101, 2, v5
	v_xor_b32_e32 v5, 8, v1
	v_cmp_lt_i32_e32 vcc, v5, v3
	v_lshlrev_b32_e32 v74, 2, v2
	v_ashrrev_i32_e32 v71, 31, v70
	v_cndmask_b32_e32 v5, v1, v5, vcc
	v_lshlrev_b32_e32 v102, 2, v5
	v_xor_b32_e32 v5, 4, v1
	v_cmp_lt_i32_e32 vcc, v5, v3
	v_mov_b32_e32 v69, v75
	v_lshl_add_u64 v[78:79], s[22:23], 0, v[74:75]
	v_cndmask_b32_e32 v5, v1, v5, vcc
	v_lshlrev_b32_e32 v103, 2, v5
	v_xor_b32_e32 v5, 2, v1
	v_cmp_lt_i32_e32 vcc, v5, v3
	v_lshlrev_b32_e32 v74, 2, v4
	v_mov_b32_e32 v73, v75
	v_cndmask_b32_e32 v5, v1, v5, vcc
	v_lshlrev_b32_e32 v104, 2, v5
	v_xor_b32_e32 v5, 1, v1
	v_cmp_lt_i32_e32 vcc, v5, v3
	s_ashr_i32 s3, s2, 31
	v_lshlrev_b64 v[8:9], 13, v[70:71]
	v_cndmask_b32_e32 v1, v1, v5, vcc
	v_lshlrev_b32_e32 v86, 2, v2
	v_lshlrev_b32_e32 v88, 2, v4
	v_lshlrev_b32_e32 v105, 2, v1
	v_lshl_add_u64 v[76:77], s[22:23], 0, v[68:69]
	v_lshl_add_u64 v[80:81], s[22:23], 0, v[74:75]
	v_lshl_add_u64 v[82:83], s[26:27], 0, v[72:73]
	v_lshl_add_u64 v[84:85], s[36:37], 0, v[8:9]
	s_lshl_b64 s[4:5], s[2:3], 13
	s_add_i32 s9, s74, s30
	s_mov_b64 s[6:7], 0
	s_movk_i32 s12, 0x7fff
	s_movk_i32 s13, 0x1080
	s_mov_b32 s8, 0x3a000000
	s_mov_b32 s14, 0x800000
	s_mov_b32 s15, 0x5fff
	v_lshlrev_b32_e32 v74, 2, v0
	v_mov_b32_e32 v90, v86
	v_mov_b32_e32 v91, v75
	v_mov_b32_e32 v92, v88
	v_mov_b32_e32 v93, v75
	v_mov_b32_e32 v94, 0x358637bd
	s_branch .Lp5pre_1191

; __device__ __forceinline__ void phase5(const Params& p) {
;     int t_ = threadIdx.x; asm volatile("" : "+v"(t_));
;     const int lane = t_ & 63, gw = blockIdx.x * 8 + (t_ >> 6), nw = gridDim.x * 8;
;     const bf16_t* DL = (const bf16_t*)(p.ws + WS_H);
;     int r = gw;
;     for (; r + nw < T; r += 2 * nw) p5_rows<2>(p, DL, r, nw, lane);
;     if (r < T) p5_rows<1>(p, DL, r, nw, lane);
.Lp5pre_1198:
	s_or_b64 exec, exec, s[0:1]
	v_mov_b32_e32 v0, v232
	s_branch .LBB0_1135

; __device__ __forceinline__ void phase5(const Params& p) {
;     int t_ = threadIdx.x; asm volatile("" : "+v"(t_));
;     const int lane = t_ & 63, gw = blockIdx.x * 8 + (t_ >> 6), nw = gridDim.x * 8;
;     const bf16_t* DL = (const bf16_t*)(p.ws + WS_H);
;     int r = gw;
;     for (; r + nw < T; r += 2 * nw) p5_rows<2>(p, DL, r, nw, lane);
;     if (r < T) p5_rows<1>(p, DL, r, nw, lane);
.LBB0_1188:
	s_or_b64 exec, exec, s[2:3]
	s_waitcnt lgkmcnt(0)
	s_barrier
	s_mov_b32 s0, 0x8800
	v_ashrrev_i32_e32 v95, 6, v0
	s_mul_i32 s1, s74, 12
	s_cmpk_gt_u32 s30, 0x5bf
	s_cselect_b32 s1, s1, 0
	s_cmpk_eq_u32 s33, 0x100
	s_cselect_b32 s1, s1, 0
	s_nop 0
	v_add_u32_e32 v95, s1, v95
	v_add_u32_e32 v70, s30, v95
	v_and_b32_e32 v1, 63, v0
	v_add_u32_e32 v6, s74, v70
	v_cmp_gt_i32_e32 vcc, s0, v6
	v_lshlrev_b32_e32 v68, 5, v1
	v_lshlrev_b32_e32 v72, 4, v1
	s_and_saveexec_b64 s[0:1], vcc
	s_cbranch_execz .LBB0_1198
	v_lshlrev_b32_e32 v0, 3, v1
	v_mbcnt_hi_u32_b32 v1, -1, v190
	v_and_b32_e32 v3, 64, v1
	v_add_u32_e32 v3, 64, v3
	v_xor_b32_e32 v5, 32, v1
	v_cmp_lt_i32_e32 vcc, v5, v3
	v_or_b32_e32 v2, 0x400, v0
	v_mov_b32_e32 v75, 0
	v_cndmask_b32_e32 v5, v1, v5, vcc
	v_lshlrev_b32_e32 v100, 2, v5
	v_xor_b32_e32 v5, 16, v1
	v_cmp_lt_i32_e32 vcc, v5, v3
	v_or_b32_e32 v4, 0x600, v0
	s_lshl_b32 s2, s33, 4
	v_cndmask_b32_e32 v5, v1, v5, vcc
	v_lshlrev_b32_e32 v101, 2, v5
	v_xor_b32_e32 v5, 8, v1
	v_cmp_lt_i32_e32 vcc, v5, v3
	v_lshlrev_b32_e32 v74, 2, v2
	v_ashrrev_i32_e32 v71, 31, v70
	v_cndmask_b32_e32 v5, v1, v5, vcc
	v_lshlrev_b32_e32 v102, 2, v5
	v_xor_b32_e32 v5, 4, v1
	v_cmp_lt_i32_e32 vcc, v5, v3
	v_mov_b32_e32 v69, v75
	v_lshl_add_u64 v[78:79], s[22:23], 0, v[74:75]
	v_cndmask_b32_e32 v5, v1, v5, vcc
	v_lshlrev_b32_e32 v103, 2, v5
	v_xor_b32_e32 v5, 2, v1
	v_cmp_lt_i32_e32 vcc, v5, v3
	v_lshlrev_b32_e32 v74, 2, v4
	v_mov_b32_e32 v73, v75
	v_cndmask_b32_e32 v5, v1, v5, vcc
	v_lshlrev_b32_e32 v104, 2, v5
	v_xor_b32_e32 v5, 1, v1
	v_cmp_lt_i32_e32 vcc, v5, v3
	s_ashr_i32 s3, s2, 31
	v_lshlrev_b64 v[8:9], 13, v[70:71]
	v_cndmask_b32_e32 v1, v1, v5, vcc
	v_lshlrev_b32_e32 v86, 2, v2
	v_lshlrev_b32_e32 v88, 2, v4
	v_lshlrev_b32_e32 v105, 2, v1
	v_lshl_add_u64 v[76:77], s[22:23], 0, v[68:69]
	v_lshl_add_u64 v[80:81], s[22:23], 0, v[74:75]
	v_lshl_add_u64 v[82:83], s[26:27], 0, v[72:73]
	v_lshl_add_u64 v[84:85], s[36:37], 0, v[8:9]
	s_lshl_b64 s[4:5], s[2:3], 13
	s_add_i32 s9, s74, s30
	s_mov_b64 s[6:7], 0
	s_movk_i32 s12, 0x7fff
	s_movk_i32 s13, 0x1080
	s_mov_b32 s8, 0x3a000000
	s_mov_b32 s14, 0x800000
	s_mov_b32 s15, 0x87ff
	v_lshlrev_b32_e32 v74, 2, v0
	v_mov_b32_e32 v90, v86
	v_mov_b32_e32 v91, v75
	v_mov_b32_e32 v92, v88
	v_mov_b32_e32 v93, v75
	v_mov_b32_e32 v94, 0x358637bd
	s_branch .LBB0_1191
